# MLP2 second half-step vmcnt fast path (branchless steady-state wait) on top of v35
# baseline (speedup 1.0000x reference)
.Ldma_m2a_2:
	s_nop 0
	ds_read_b128 v[110:113], v133 offset:2048
	v_mfma_f32_16x16x32_bf16 v[26:29], v[0:3], v[98:101], v[26:29]
	v_mfma_f32_16x16x32_bf16 v[30:33], v[4:7], v[98:101], v[30:33]
	v_mfma_f32_16x16x32_bf16 v[78:81], v[8:11], v[98:101], v[78:81]
	v_mfma_f32_16x16x32_bf16 v[58:61], v[12:15], v[98:101], v[58:61]
	ds_read_b128 v[98:101], v133 offset:3072
	s_nop 0
	s_waitcnt lgkmcnt(2)
	v_mfma_f32_16x16x32_bf16 v[86:89], v[106:109], v[22:25], v[86:89]
	v_mfma_f32_16x16x32_bf16 v[82:85], v[102:105], v[22:25], v[82:85]
	v_mfma_f32_16x16x32_bf16 v[74:77], v[94:97], v[22:25], v[74:77]
	v_mfma_f32_16x16x32_bf16 v[66:69], v[90:93], v[22:25], v[66:69]
	v_mfma_f32_16x16x32_bf16 v[54:57], v[106:109], v[18:21], v[54:57]
	v_mfma_f32_16x16x32_bf16 v[46:49], v[102:105], v[18:21], v[46:49]
	v_mfma_f32_16x16x32_bf16 v[38:41], v[94:97], v[18:21], v[38:41]
	v_mfma_f32_16x16x32_bf16 v[34:37], v[90:93], v[18:21], v[34:37]
	s_cbranch_vccnz .LBB0_1276
	s_cmp_lt_u32 s52, 4
	s_cbranch_scc1 .Lvw_m2b
	s_waitcnt vmcnt(12)

.Lvw_m2b:
	s_min_u32 s46, s52, 4
	s_cmp_lg_u32 s46, 4
	s_mov_b64 s[46:47], -1
	s_cbranch_scc0 .LBB0_1274
	s_mov_b64 s[50:51], -1
	s_mov_b64 s[46:47], 0
	s_cmpk_lt_i32 s53, 0x7c
	s_mov_b64 s[48:49], 0
	s_cbranch_scc0 .LBB0_1280
	s_and_b64 vcc, exec, s[50:51]
	s_cbranch_vccnz .LBB0_1283

.LBB0_1274:
	s_and_b64 vcc, exec, s[46:47]
	s_cbranch_vccz .LBB0_1276
	s_waitcnt vmcnt(12)
	s_branch .LBB0_1276
